# hand-written P0b (S5 kernel taps) built from LDS-staged tables instead of 64 iterations of small dependent global loads
# speedup vs baseline: 1.0098x; 1.0024x over previous
.LBB0_151:
	s_load_dwordx2 s[4:5], s[78:79], 0x100
	s_load_dwordx2 s[8:9], s[78:79], 0x70
	s_load_dwordx2 s[10:11], s[78:79], 0x78
	v_readfirstlane_b32 s12, v224
	s_lshr_b32 s12, s12, 6
	s_lshr_b32 s13, s2, 2
	s_lshr_b32 s14, s13, 5
	s_lshr_b32 s15, s13, 1
	s_and_b32 s16, s13, 31
	s_and_b32 s17, s2, 3
	s_lshl_b32 s17, s17, 3
	s_add_u32 s17, s17, s12
	v_lshlrev_b32_e32 v0, 4, v224
	v_lshlrev_b32_e32 v1, 2, v224
	v_add_u32_e32 v2, 0x800, v1
	s_mul_i32 s18, s14, 0x1c4000
	s_waitcnt lgkmcnt(0)
	s_add_u32 s6, s4, s18
	s_addc_u32 s7, s5, 0
	s_add_u32 s6, s6, 0x6040000
	s_addc_u32 s7, s7, 0
	s_lshl_b32 s18, s15, 12
	s_add_u32 s8, s8, s18
	s_addc_u32 s9, s9, 0
	s_add_u32 s10, s10, s18
	s_addc_u32 s11, s11, 0
	global_load_dword v24, v1, s[8:9]
	global_load_dword v25, v1, s[10:11]
	global_load_dword v26, v2, s[8:9]
	global_load_dword v27, v2, s[10:11]
	s_lshl_b32 s18, s16, 13
	s_add_u32 s8, s6, s18
	s_addc_u32 s9, s7, 0
	s_add_u32 s8, s8, 0x84000
	s_addc_u32 s9, s9, 0
	global_load_dwordx4 v[18:21], v0, s[8:9]
	s_mul_i32 s18, s16, 0x4200
	s_add_u32 s8, s6, s18
	s_addc_u32 s9, s7, 0
	global_load_dwordx4 v[6:9], v0, s[8:9]
	s_add_u32 s10, s8, 0x2000
	s_addc_u32 s11, s9, 0
	global_load_dwordx4 v[10:13], v0, s[10:11]
	s_cmp_eq_u32 s12, 0
	s_cbranch_scc0 .Ltaps_a
	s_mov_b32 exec_hi, 0
	s_add_u32 s10, s8, 0x4000
	s_addc_u32 s11, s9, 0
	global_load_dwordx4 v[14:17], v0, s[10:11]
	s_mov_b32 exec_hi, -1
.Ltaps_a:
	v_mov_b32_e32 v3, v224
	v_add_u32_e32 v4, 512, v224
	v_lshrrev_b32_e32 v5, 6, v3
	v_and_b32_e32 v3, 63, v3
	v_lshl_add_u32 v3, v3, 4, v5
	v_lshlrev_b32_e32 v3, 3, v3
	v_add_u32_e32 v3, 0x17400, v3
	v_lshrrev_b32_e32 v5, 6, v4
	v_and_b32_e32 v4, 63, v4
	v_lshl_add_u32 v4, v4, 4, v5
	v_lshlrev_b32_e32 v4, 3, v4
	v_add_u32_e32 v4, 0x17400, v4
	s_waitcnt vmcnt(0)
	ds_write_b64 v3, v[24:25]
	ds_write_b64 v4, v[26:27]
	v_add_u32_e32 v5, 0x15400, v0
	ds_write_b128 v5, v[18:21]
	v_add_u32_e32 v5, 0x11000, v0
	ds_write_b128 v5, v[6:9]
	ds_write_b128 v5, v[10:13] offset:8192
	s_cmp_eq_u32 s12, 0
	s_cbranch_scc0 .Ltaps_b
	s_mov_b32 exec_hi, 0
	ds_write_b128 v5, v[14:17] offset:16384
	s_mov_b32 exec_hi, -1
.Ltaps_b:
	s_waitcnt lgkmcnt(0)
	s_barrier
	v_and_b32_e32 v7, 3, v224
	v_lshlrev_b32_e32 v7, 5, v7
	v_add_u32_e32 v7, 0x15400, v7
	v_bfe_u32 v8, v224, 2, 4
	v_lshlrev_b32_e32 v8, 3, v8
	v_add_u32_e32 v8, 0x17400, v8
	s_lshl_b32 s18, s17, 3
	s_add_u32 s18, s18, 0x11000
	v_mov_b32_e32 v6, s18
	v_mov_b32_e32 v10, 0
	v_mov_b32_e32 v11, 0
	v_mov_b32_e32 v12, 0
	v_mov_b32_e32 v13, 0
	ds_read_b64 v[14:15], v6
	ds_read_b64 v[20:21], v8
	ds_read_b128 v[16:19], v7
	ds_read_b128 v[24:27], v7 offset:16
	ds_read_b64 v[28:29], v6 offset:264
	ds_read_b64 v[38:39], v8 offset:128
	ds_read_b128 v[30:33], v7 offset:128
	ds_read_b128 v[34:37], v7 offset:144
	ds_read_b64 v[40:41], v6 offset:528
	ds_read_b64 v[46:47], v8 offset:256
	ds_read_b128 v[42:45], v7 offset:256
	ds_read_b128 v[50:53], v7 offset:272
	s_waitcnt lgkmcnt(8)
	v_mul_f32_e32 v55, v21, v15
	v_mul_f32_e32 v56, v21, v14
	v_fma_f32 v22, v20, v14, -v55
	v_fma_f32 v54, v20, v15, v56
	v_fma_f32 v10, v22, v16, v10
	v_fma_f32 v11, v22, v18, v11
	v_fma_f32 v12, v22, v24, v12
	v_fma_f32 v13, v22, v26, v13
	v_fma_f32 v10, -v54, v17, v10
	v_fma_f32 v11, -v54, v19, v11
	v_fma_f32 v12, -v54, v25, v12
	v_fma_f32 v13, -v54, v27, v13
	ds_read_b64 v[14:15], v6 offset:792
	ds_read_b64 v[20:21], v8 offset:384
	ds_read_b128 v[16:19], v7 offset:384
	ds_read_b128 v[24:27], v7 offset:400
	s_waitcnt lgkmcnt(8)
	v_mul_f32_e32 v55, v39, v29
	v_mul_f32_e32 v56, v39, v28
	v_fma_f32 v22, v38, v28, -v55
	v_fma_f32 v54, v38, v29, v56
	v_fma_f32 v10, v22, v30, v10
	v_fma_f32 v11, v22, v32, v11
	v_fma_f32 v12, v22, v34, v12
	v_fma_f32 v13, v22, v36, v13
	v_fma_f32 v10, -v54, v31, v10
	v_fma_f32 v11, -v54, v33, v11
	v_fma_f32 v12, -v54, v35, v12
	v_fma_f32 v13, -v54, v37, v13
	ds_read_b64 v[28:29], v6 offset:1056
	ds_read_b64 v[38:39], v8 offset:512
	ds_read_b128 v[30:33], v7 offset:512
	ds_read_b128 v[34:37], v7 offset:528
	s_waitcnt lgkmcnt(8)
	v_mul_f32_e32 v55, v47, v41
	v_mul_f32_e32 v56, v47, v40
	v_fma_f32 v22, v46, v40, -v55
	v_fma_f32 v54, v46, v41, v56
	v_fma_f32 v10, v22, v42, v10
	v_fma_f32 v11, v22, v44, v11
	v_fma_f32 v12, v22, v50, v12
	v_fma_f32 v13, v22, v52, v13
	v_fma_f32 v10, -v54, v43, v10
	v_fma_f32 v11, -v54, v45, v11
	v_fma_f32 v12, -v54, v51, v12
	v_fma_f32 v13, -v54, v53, v13
	ds_read_b64 v[40:41], v6 offset:1320
	ds_read_b64 v[46:47], v8 offset:640
	ds_read_b128 v[42:45], v7 offset:640
	ds_read_b128 v[50:53], v7 offset:656
	s_waitcnt lgkmcnt(8)
	v_mul_f32_e32 v55, v21, v15
	v_mul_f32_e32 v56, v21, v14
	v_fma_f32 v22, v20, v14, -v55
	v_fma_f32 v54, v20, v15, v56
	v_fma_f32 v10, v22, v16, v10
	v_fma_f32 v11, v22, v18, v11
	v_fma_f32 v12, v22, v24, v12
	v_fma_f32 v13, v22, v26, v13
	v_fma_f32 v10, -v54, v17, v10
	v_fma_f32 v11, -v54, v19, v11
	v_fma_f32 v12, -v54, v25, v12
	v_fma_f32 v13, -v54, v27, v13
	ds_read_b64 v[14:15], v6 offset:1584
	ds_read_b64 v[20:21], v8 offset:768
	ds_read_b128 v[16:19], v7 offset:768
	ds_read_b128 v[24:27], v7 offset:784
	s_waitcnt lgkmcnt(8)
	v_mul_f32_e32 v55, v39, v29
	v_mul_f32_e32 v56, v39, v28
	v_fma_f32 v22, v38, v28, -v55
	v_fma_f32 v54, v38, v29, v56
	v_fma_f32 v10, v22, v30, v10
	v_fma_f32 v11, v22, v32, v11
	v_fma_f32 v12, v22, v34, v12
	v_fma_f32 v13, v22, v36, v13
	v_fma_f32 v10, -v54, v31, v10
	v_fma_f32 v11, -v54, v33, v11
	v_fma_f32 v12, -v54, v35, v12
	v_fma_f32 v13, -v54, v37, v13
	ds_read_b64 v[28:29], v6 offset:1848
	ds_read_b64 v[38:39], v8 offset:896
	ds_read_b128 v[30:33], v7 offset:896
	ds_read_b128 v[34:37], v7 offset:912
	s_waitcnt lgkmcnt(8)
	v_mul_f32_e32 v55, v47, v41
	v_mul_f32_e32 v56, v47, v40
	v_fma_f32 v22, v46, v40, -v55
	v_fma_f32 v54, v46, v41, v56
	v_fma_f32 v10, v22, v42, v10
	v_fma_f32 v11, v22, v44, v11
	v_fma_f32 v12, v22, v50, v12
	v_fma_f32 v13, v22, v52, v13
	v_fma_f32 v10, -v54, v43, v10
	v_fma_f32 v11, -v54, v45, v11
	v_fma_f32 v12, -v54, v51, v12
	v_fma_f32 v13, -v54, v53, v13
	ds_read_b64 v[40:41], v6 offset:2112
	ds_read_b64 v[46:47], v8 offset:1024
	ds_read_b128 v[42:45], v7 offset:1024
	ds_read_b128 v[50:53], v7 offset:1040
	s_waitcnt lgkmcnt(8)
	v_mul_f32_e32 v55, v21, v15
	v_mul_f32_e32 v56, v21, v14
	v_fma_f32 v22, v20, v14, -v55
	v_fma_f32 v54, v20, v15, v56
	v_fma_f32 v10, v22, v16, v10
	v_fma_f32 v11, v22, v18, v11
	v_fma_f32 v12, v22, v24, v12
	v_fma_f32 v13, v22, v26, v13
	v_fma_f32 v10, -v54, v17, v10
	v_fma_f32 v11, -v54, v19, v11
	v_fma_f32 v12, -v54, v25, v12
	v_fma_f32 v13, -v54, v27, v13
	ds_read_b64 v[14:15], v6 offset:2376
	ds_read_b64 v[20:21], v8 offset:1152
	ds_read_b128 v[16:19], v7 offset:1152
	ds_read_b128 v[24:27], v7 offset:1168
	s_waitcnt lgkmcnt(8)
	v_mul_f32_e32 v55, v39, v29
	v_mul_f32_e32 v56, v39, v28
	v_fma_f32 v22, v38, v28, -v55
	v_fma_f32 v54, v38, v29, v56
	v_fma_f32 v10, v22, v30, v10
	v_fma_f32 v11, v22, v32, v11
	v_fma_f32 v12, v22, v34, v12
	v_fma_f32 v13, v22, v36, v13
	v_fma_f32 v10, -v54, v31, v10
	v_fma_f32 v11, -v54, v33, v11
	v_fma_f32 v12, -v54, v35, v12
	v_fma_f32 v13, -v54, v37, v13
	ds_read_b64 v[28:29], v6 offset:2640
	ds_read_b64 v[38:39], v8 offset:1280
	ds_read_b128 v[30:33], v7 offset:1280
	ds_read_b128 v[34:37], v7 offset:1296
	s_waitcnt lgkmcnt(8)
	v_mul_f32_e32 v55, v47, v41
	v_mul_f32_e32 v56, v47, v40
	v_fma_f32 v22, v46, v40, -v55
	v_fma_f32 v54, v46, v41, v56
	v_fma_f32 v10, v22, v42, v10
	v_fma_f32 v11, v22, v44, v11
	v_fma_f32 v12, v22, v50, v12
	v_fma_f32 v13, v22, v52, v13
	v_fma_f32 v10, -v54, v43, v10
	v_fma_f32 v11, -v54, v45, v11
	v_fma_f32 v12, -v54, v51, v12
	v_fma_f32 v13, -v54, v53, v13
	ds_read_b64 v[40:41], v6 offset:2904
	ds_read_b64 v[46:47], v8 offset:1408
	ds_read_b128 v[42:45], v7 offset:1408
	ds_read_b128 v[50:53], v7 offset:1424
	s_waitcnt lgkmcnt(8)
	v_mul_f32_e32 v55, v21, v15
	v_mul_f32_e32 v56, v21, v14
	v_fma_f32 v22, v20, v14, -v55
	v_fma_f32 v54, v20, v15, v56
	v_fma_f32 v10, v22, v16, v10
	v_fma_f32 v11, v22, v18, v11
	v_fma_f32 v12, v22, v24, v12
	v_fma_f32 v13, v22, v26, v13
	v_fma_f32 v10, -v54, v17, v10
	v_fma_f32 v11, -v54, v19, v11
	v_fma_f32 v12, -v54, v25, v12
	v_fma_f32 v13, -v54, v27, v13
	ds_read_b64 v[14:15], v6 offset:3168
	ds_read_b64 v[20:21], v8 offset:1536
	ds_read_b128 v[16:19], v7 offset:1536
	ds_read_b128 v[24:27], v7 offset:1552
	s_waitcnt lgkmcnt(8)
	v_mul_f32_e32 v55, v39, v29
	v_mul_f32_e32 v56, v39, v28
	v_fma_f32 v22, v38, v28, -v55
	v_fma_f32 v54, v38, v29, v56
	v_fma_f32 v10, v22, v30, v10
	v_fma_f32 v11, v22, v32, v11
	v_fma_f32 v12, v22, v34, v12
	v_fma_f32 v13, v22, v36, v13
	v_fma_f32 v10, -v54, v31, v10
	v_fma_f32 v11, -v54, v33, v11
	v_fma_f32 v12, -v54, v35, v12
	v_fma_f32 v13, -v54, v37, v13
	ds_read_b64 v[28:29], v6 offset:3432
	ds_read_b64 v[38:39], v8 offset:1664
	ds_read_b128 v[30:33], v7 offset:1664
	ds_read_b128 v[34:37], v7 offset:1680
	s_waitcnt lgkmcnt(8)
	v_mul_f32_e32 v55, v47, v41
	v_mul_f32_e32 v56, v47, v40
	v_fma_f32 v22, v46, v40, -v55
	v_fma_f32 v54, v46, v41, v56
	v_fma_f32 v10, v22, v42, v10
	v_fma_f32 v11, v22, v44, v11
	v_fma_f32 v12, v22, v50, v12
	v_fma_f32 v13, v22, v52, v13
	v_fma_f32 v10, -v54, v43, v10
	v_fma_f32 v11, -v54, v45, v11
	v_fma_f32 v12, -v54, v51, v12
	v_fma_f32 v13, -v54, v53, v13
	ds_read_b64 v[40:41], v6 offset:3696
	ds_read_b64 v[46:47], v8 offset:1792
	ds_read_b128 v[42:45], v7 offset:1792
	ds_read_b128 v[50:53], v7 offset:1808
	s_waitcnt lgkmcnt(8)
	v_mul_f32_e32 v55, v21, v15
	v_mul_f32_e32 v56, v21, v14
	v_fma_f32 v22, v20, v14, -v55
	v_fma_f32 v54, v20, v15, v56
	v_fma_f32 v10, v22, v16, v10
	v_fma_f32 v11, v22, v18, v11
	v_fma_f32 v12, v22, v24, v12
	v_fma_f32 v13, v22, v26, v13
	v_fma_f32 v10, -v54, v17, v10
	v_fma_f32 v11, -v54, v19, v11
	v_fma_f32 v12, -v54, v25, v12
	v_fma_f32 v13, -v54, v27, v13
	ds_read_b64 v[14:15], v6 offset:3960
	ds_read_b64 v[20:21], v8 offset:1920
	ds_read_b128 v[16:19], v7 offset:1920
	ds_read_b128 v[24:27], v7 offset:1936
	s_waitcnt lgkmcnt(8)
	v_mul_f32_e32 v55, v39, v29
	v_mul_f32_e32 v56, v39, v28
	v_fma_f32 v22, v38, v28, -v55
	v_fma_f32 v54, v38, v29, v56
	v_fma_f32 v10, v22, v30, v10
	v_fma_f32 v11, v22, v32, v11
	v_fma_f32 v12, v22, v34, v12
	v_fma_f32 v13, v22, v36, v13
	v_fma_f32 v10, -v54, v31, v10
	v_fma_f32 v11, -v54, v33, v11
	v_fma_f32 v12, -v54, v35, v12
	v_fma_f32 v13, -v54, v37, v13
	ds_read_b64 v[28:29], v6 offset:4224
	ds_read_b64 v[38:39], v8 offset:2048
	ds_read_b128 v[30:33], v7 offset:2048
	ds_read_b128 v[34:37], v7 offset:2064
	s_waitcnt lgkmcnt(8)
	v_mul_f32_e32 v55, v47, v41
	v_mul_f32_e32 v56, v47, v40
	v_fma_f32 v22, v46, v40, -v55
	v_fma_f32 v54, v46, v41, v56
	v_fma_f32 v10, v22, v42, v10
	v_fma_f32 v11, v22, v44, v11
	v_fma_f32 v12, v22, v50, v12
	v_fma_f32 v13, v22, v52, v13
	v_fma_f32 v10, -v54, v43, v10
	v_fma_f32 v11, -v54, v45, v11
	v_fma_f32 v12, -v54, v51, v12
	v_fma_f32 v13, -v54, v53, v13
	ds_read_b64 v[40:41], v6 offset:4488
	ds_read_b64 v[46:47], v8 offset:2176
	ds_read_b128 v[42:45], v7 offset:2176
	ds_read_b128 v[50:53], v7 offset:2192
	s_waitcnt lgkmcnt(8)
	v_mul_f32_e32 v55, v21, v15
	v_mul_f32_e32 v56, v21, v14
	v_fma_f32 v22, v20, v14, -v55
	v_fma_f32 v54, v20, v15, v56
	v_fma_f32 v10, v22, v16, v10
	v_fma_f32 v11, v22, v18, v11
	v_fma_f32 v12, v22, v24, v12
	v_fma_f32 v13, v22, v26, v13
	v_fma_f32 v10, -v54, v17, v10
	v_fma_f32 v11, -v54, v19, v11
	v_fma_f32 v12, -v54, v25, v12
	v_fma_f32 v13, -v54, v27, v13
	ds_read_b64 v[14:15], v6 offset:4752
	ds_read_b64 v[20:21], v8 offset:2304
	ds_read_b128 v[16:19], v7 offset:2304
	ds_read_b128 v[24:27], v7 offset:2320
	s_waitcnt lgkmcnt(8)
	v_mul_f32_e32 v55, v39, v29
	v_mul_f32_e32 v56, v39, v28
	v_fma_f32 v22, v38, v28, -v55
	v_fma_f32 v54, v38, v29, v56
	v_fma_f32 v10, v22, v30, v10
	v_fma_f32 v11, v22, v32, v11
	v_fma_f32 v12, v22, v34, v12
	v_fma_f32 v13, v22, v36, v13
	v_fma_f32 v10, -v54, v31, v10
	v_fma_f32 v11, -v54, v33, v11
	v_fma_f32 v12, -v54, v35, v12
	v_fma_f32 v13, -v54, v37, v13
	ds_read_b64 v[28:29], v6 offset:5016
	ds_read_b64 v[38:39], v8 offset:2432
	ds_read_b128 v[30:33], v7 offset:2432
	ds_read_b128 v[34:37], v7 offset:2448
	s_waitcnt lgkmcnt(8)
	v_mul_f32_e32 v55, v47, v41
	v_mul_f32_e32 v56, v47, v40
	v_fma_f32 v22, v46, v40, -v55
	v_fma_f32 v54, v46, v41, v56
	v_fma_f32 v10, v22, v42, v10
	v_fma_f32 v11, v22, v44, v11
	v_fma_f32 v12, v22, v50, v12
	v_fma_f32 v13, v22, v52, v13
	v_fma_f32 v10, -v54, v43, v10
	v_fma_f32 v11, -v54, v45, v11
	v_fma_f32 v12, -v54, v51, v12
	v_fma_f32 v13, -v54, v53, v13
	ds_read_b64 v[40:41], v6 offset:5280
	ds_read_b64 v[46:47], v8 offset:2560
	ds_read_b128 v[42:45], v7 offset:2560
	ds_read_b128 v[50:53], v7 offset:2576
	s_waitcnt lgkmcnt(8)
	v_mul_f32_e32 v55, v21, v15
	v_mul_f32_e32 v56, v21, v14
	v_fma_f32 v22, v20, v14, -v55
	v_fma_f32 v54, v20, v15, v56
	v_fma_f32 v10, v22, v16, v10
	v_fma_f32 v11, v22, v18, v11
	v_fma_f32 v12, v22, v24, v12
	v_fma_f32 v13, v22, v26, v13
	v_fma_f32 v10, -v54, v17, v10
	v_fma_f32 v11, -v54, v19, v11
	v_fma_f32 v12, -v54, v25, v12
	v_fma_f32 v13, -v54, v27, v13
	ds_read_b64 v[14:15], v6 offset:5544
	ds_read_b64 v[20:21], v8 offset:2688
	ds_read_b128 v[16:19], v7 offset:2688
	ds_read_b128 v[24:27], v7 offset:2704
	s_waitcnt lgkmcnt(8)
	v_mul_f32_e32 v55, v39, v29
	v_mul_f32_e32 v56, v39, v28
	v_fma_f32 v22, v38, v28, -v55
	v_fma_f32 v54, v38, v29, v56
	v_fma_f32 v10, v22, v30, v10
	v_fma_f32 v11, v22, v32, v11
	v_fma_f32 v12, v22, v34, v12
	v_fma_f32 v13, v22, v36, v13
	v_fma_f32 v10, -v54, v31, v10
	v_fma_f32 v11, -v54, v33, v11
	v_fma_f32 v12, -v54, v35, v12
	v_fma_f32 v13, -v54, v37, v13
	ds_read_b64 v[28:29], v6 offset:5808
	ds_read_b64 v[38:39], v8 offset:2816
	ds_read_b128 v[30:33], v7 offset:2816
	ds_read_b128 v[34:37], v7 offset:2832
	s_waitcnt lgkmcnt(8)
	v_mul_f32_e32 v55, v47, v41
	v_mul_f32_e32 v56, v47, v40
	v_fma_f32 v22, v46, v40, -v55
	v_fma_f32 v54, v46, v41, v56
	v_fma_f32 v10, v22, v42, v10
	v_fma_f32 v11, v22, v44, v11
	v_fma_f32 v12, v22, v50, v12
	v_fma_f32 v13, v22, v52, v13
	v_fma_f32 v10, -v54, v43, v10
	v_fma_f32 v11, -v54, v45, v11
	v_fma_f32 v12, -v54, v51, v12
	v_fma_f32 v13, -v54, v53, v13
	ds_read_b64 v[40:41], v6 offset:6072
	ds_read_b64 v[46:47], v8 offset:2944
	ds_read_b128 v[42:45], v7 offset:2944
	ds_read_b128 v[50:53], v7 offset:2960
	s_waitcnt lgkmcnt(8)
	v_mul_f32_e32 v55, v21, v15
	v_mul_f32_e32 v56, v21, v14
	v_fma_f32 v22, v20, v14, -v55
	v_fma_f32 v54, v20, v15, v56
	v_fma_f32 v10, v22, v16, v10
	v_fma_f32 v11, v22, v18, v11
	v_fma_f32 v12, v22, v24, v12
	v_fma_f32 v13, v22, v26, v13
	v_fma_f32 v10, -v54, v17, v10
	v_fma_f32 v11, -v54, v19, v11
	v_fma_f32 v12, -v54, v25, v12
	v_fma_f32 v13, -v54, v27, v13
	ds_read_b64 v[14:15], v6 offset:6336
	ds_read_b64 v[20:21], v8 offset:3072
	ds_read_b128 v[16:19], v7 offset:3072
	ds_read_b128 v[24:27], v7 offset:3088
	s_waitcnt lgkmcnt(8)
	v_mul_f32_e32 v55, v39, v29
	v_mul_f32_e32 v56, v39, v28
	v_fma_f32 v22, v38, v28, -v55
	v_fma_f32 v54, v38, v29, v56
	v_fma_f32 v10, v22, v30, v10
	v_fma_f32 v11, v22, v32, v11
	v_fma_f32 v12, v22, v34, v12
	v_fma_f32 v13, v22, v36, v13
	v_fma_f32 v10, -v54, v31, v10
	v_fma_f32 v11, -v54, v33, v11
	v_fma_f32 v12, -v54, v35, v12
	v_fma_f32 v13, -v54, v37, v13
	ds_read_b64 v[28:29], v6 offset:6600
	ds_read_b64 v[38:39], v8 offset:3200
	ds_read_b128 v[30:33], v7 offset:3200
	ds_read_b128 v[34:37], v7 offset:3216
	s_waitcnt lgkmcnt(8)
	v_mul_f32_e32 v55, v47, v41
	v_mul_f32_e32 v56, v47, v40
	v_fma_f32 v22, v46, v40, -v55
	v_fma_f32 v54, v46, v41, v56
	v_fma_f32 v10, v22, v42, v10
	v_fma_f32 v11, v22, v44, v11
	v_fma_f32 v12, v22, v50, v12
	v_fma_f32 v13, v22, v52, v13
	v_fma_f32 v10, -v54, v43, v10
	v_fma_f32 v11, -v54, v45, v11
	v_fma_f32 v12, -v54, v51, v12
	v_fma_f32 v13, -v54, v53, v13
	ds_read_b64 v[40:41], v6 offset:6864
	ds_read_b64 v[46:47], v8 offset:3328
	ds_read_b128 v[42:45], v7 offset:3328
	ds_read_b128 v[50:53], v7 offset:3344
	s_waitcnt lgkmcnt(8)
	v_mul_f32_e32 v55, v21, v15
	v_mul_f32_e32 v56, v21, v14
	v_fma_f32 v22, v20, v14, -v55
	v_fma_f32 v54, v20, v15, v56
	v_fma_f32 v10, v22, v16, v10
	v_fma_f32 v11, v22, v18, v11
	v_fma_f32 v12, v22, v24, v12
	v_fma_f32 v13, v22, v26, v13
	v_fma_f32 v10, -v54, v17, v10
	v_fma_f32 v11, -v54, v19, v11
	v_fma_f32 v12, -v54, v25, v12
	v_fma_f32 v13, -v54, v27, v13
	ds_read_b64 v[14:15], v6 offset:7128
	ds_read_b64 v[20:21], v8 offset:3456
	ds_read_b128 v[16:19], v7 offset:3456
	ds_read_b128 v[24:27], v7 offset:3472
	s_waitcnt lgkmcnt(8)
	v_mul_f32_e32 v55, v39, v29
	v_mul_f32_e32 v56, v39, v28
	v_fma_f32 v22, v38, v28, -v55
	v_fma_f32 v54, v38, v29, v56
	v_fma_f32 v10, v22, v30, v10
	v_fma_f32 v11, v22, v32, v11
	v_fma_f32 v12, v22, v34, v12
	v_fma_f32 v13, v22, v36, v13
	v_fma_f32 v10, -v54, v31, v10
	v_fma_f32 v11, -v54, v33, v11
	v_fma_f32 v12, -v54, v35, v12
	v_fma_f32 v13, -v54, v37, v13
	ds_read_b64 v[28:29], v6 offset:7392
	ds_read_b64 v[38:39], v8 offset:3584
	ds_read_b128 v[30:33], v7 offset:3584
	ds_read_b128 v[34:37], v7 offset:3600
	s_waitcnt lgkmcnt(8)
	v_mul_f32_e32 v55, v47, v41
	v_mul_f32_e32 v56, v47, v40
	v_fma_f32 v22, v46, v40, -v55
	v_fma_f32 v54, v46, v41, v56
	v_fma_f32 v10, v22, v42, v10
	v_fma_f32 v11, v22, v44, v11
	v_fma_f32 v12, v22, v50, v12
	v_fma_f32 v13, v22, v52, v13
	v_fma_f32 v10, -v54, v43, v10
	v_fma_f32 v11, -v54, v45, v11
	v_fma_f32 v12, -v54, v51, v12
	v_fma_f32 v13, -v54, v53, v13
	ds_read_b64 v[40:41], v6 offset:7656
	ds_read_b64 v[46:47], v8 offset:3712
	ds_read_b128 v[42:45], v7 offset:3712
	ds_read_b128 v[50:53], v7 offset:3728
	s_waitcnt lgkmcnt(8)
	v_mul_f32_e32 v55, v21, v15
	v_mul_f32_e32 v56, v21, v14
	v_fma_f32 v22, v20, v14, -v55
	v_fma_f32 v54, v20, v15, v56
	v_fma_f32 v10, v22, v16, v10
	v_fma_f32 v11, v22, v18, v11
	v_fma_f32 v12, v22, v24, v12
	v_fma_f32 v13, v22, v26, v13
	v_fma_f32 v10, -v54, v17, v10
	v_fma_f32 v11, -v54, v19, v11
	v_fma_f32 v12, -v54, v25, v12
	v_fma_f32 v13, -v54, v27, v13
	ds_read_b64 v[14:15], v6 offset:7920
	ds_read_b64 v[20:21], v8 offset:3840
	ds_read_b128 v[16:19], v7 offset:3840
	ds_read_b128 v[24:27], v7 offset:3856
	s_waitcnt lgkmcnt(8)
	v_mul_f32_e32 v55, v39, v29
	v_mul_f32_e32 v56, v39, v28
	v_fma_f32 v22, v38, v28, -v55
	v_fma_f32 v54, v38, v29, v56
	v_fma_f32 v10, v22, v30, v10
	v_fma_f32 v11, v22, v32, v11
	v_fma_f32 v12, v22, v34, v12
	v_fma_f32 v13, v22, v36, v13
	v_fma_f32 v10, -v54, v31, v10
	v_fma_f32 v11, -v54, v33, v11
	v_fma_f32 v12, -v54, v35, v12
	v_fma_f32 v13, -v54, v37, v13
	ds_read_b64 v[28:29], v6 offset:8184
	ds_read_b64 v[38:39], v8 offset:3968
	ds_read_b128 v[30:33], v7 offset:3968
	ds_read_b128 v[34:37], v7 offset:3984
	s_waitcnt lgkmcnt(8)
	v_mul_f32_e32 v55, v47, v41
	v_mul_f32_e32 v56, v47, v40
	v_fma_f32 v22, v46, v40, -v55
	v_fma_f32 v54, v46, v41, v56
	v_fma_f32 v10, v22, v42, v10
	v_fma_f32 v11, v22, v44, v11
	v_fma_f32 v12, v22, v50, v12
	v_fma_f32 v13, v22, v52, v13
	v_fma_f32 v10, -v54, v43, v10
	v_fma_f32 v11, -v54, v45, v11
	v_fma_f32 v12, -v54, v51, v12
	v_fma_f32 v13, -v54, v53, v13
	ds_read_b64 v[40:41], v6 offset:8448
	ds_read_b64 v[46:47], v8 offset:4096
	ds_read_b128 v[42:45], v7 offset:4096
	ds_read_b128 v[50:53], v7 offset:4112
	s_waitcnt lgkmcnt(8)
	v_mul_f32_e32 v55, v21, v15
	v_mul_f32_e32 v56, v21, v14
	v_fma_f32 v22, v20, v14, -v55
	v_fma_f32 v54, v20, v15, v56
	v_fma_f32 v10, v22, v16, v10
	v_fma_f32 v11, v22, v18, v11
	v_fma_f32 v12, v22, v24, v12
	v_fma_f32 v13, v22, v26, v13
	v_fma_f32 v10, -v54, v17, v10
	v_fma_f32 v11, -v54, v19, v11
	v_fma_f32 v12, -v54, v25, v12
	v_fma_f32 v13, -v54, v27, v13
	ds_read_b64 v[14:15], v6 offset:8712
	ds_read_b64 v[20:21], v8 offset:4224
	ds_read_b128 v[16:19], v7 offset:4224
	ds_read_b128 v[24:27], v7 offset:4240
	s_waitcnt lgkmcnt(8)
	v_mul_f32_e32 v55, v39, v29
	v_mul_f32_e32 v56, v39, v28
	v_fma_f32 v22, v38, v28, -v55
	v_fma_f32 v54, v38, v29, v56
	v_fma_f32 v10, v22, v30, v10
	v_fma_f32 v11, v22, v32, v11
	v_fma_f32 v12, v22, v34, v12
	v_fma_f32 v13, v22, v36, v13
	v_fma_f32 v10, -v54, v31, v10
	v_fma_f32 v11, -v54, v33, v11
	v_fma_f32 v12, -v54, v35, v12
	v_fma_f32 v13, -v54, v37, v13
	ds_read_b64 v[28:29], v6 offset:8976
	ds_read_b64 v[38:39], v8 offset:4352
	ds_read_b128 v[30:33], v7 offset:4352
	ds_read_b128 v[34:37], v7 offset:4368
	s_waitcnt lgkmcnt(8)
	v_mul_f32_e32 v55, v47, v41
	v_mul_f32_e32 v56, v47, v40
	v_fma_f32 v22, v46, v40, -v55
	v_fma_f32 v54, v46, v41, v56
	v_fma_f32 v10, v22, v42, v10
	v_fma_f32 v11, v22, v44, v11
	v_fma_f32 v12, v22, v50, v12
	v_fma_f32 v13, v22, v52, v13
	v_fma_f32 v10, -v54, v43, v10
	v_fma_f32 v11, -v54, v45, v11
	v_fma_f32 v12, -v54, v51, v12
	v_fma_f32 v13, -v54, v53, v13
	ds_read_b64 v[40:41], v6 offset:9240
	ds_read_b64 v[46:47], v8 offset:4480
	ds_read_b128 v[42:45], v7 offset:4480
	ds_read_b128 v[50:53], v7 offset:4496
	s_waitcnt lgkmcnt(8)
	v_mul_f32_e32 v55, v21, v15
	v_mul_f32_e32 v56, v21, v14
	v_fma_f32 v22, v20, v14, -v55
	v_fma_f32 v54, v20, v15, v56
	v_fma_f32 v10, v22, v16, v10
	v_fma_f32 v11, v22, v18, v11
	v_fma_f32 v12, v22, v24, v12
	v_fma_f32 v13, v22, v26, v13
	v_fma_f32 v10, -v54, v17, v10
	v_fma_f32 v11, -v54, v19, v11
	v_fma_f32 v12, -v54, v25, v12
	v_fma_f32 v13, -v54, v27, v13
	ds_read_b64 v[14:15], v6 offset:9504
	ds_read_b64 v[20:21], v8 offset:4608
	ds_read_b128 v[16:19], v7 offset:4608
	ds_read_b128 v[24:27], v7 offset:4624
	s_waitcnt lgkmcnt(8)
	v_mul_f32_e32 v55, v39, v29
	v_mul_f32_e32 v56, v39, v28
	v_fma_f32 v22, v38, v28, -v55
	v_fma_f32 v54, v38, v29, v56
	v_fma_f32 v10, v22, v30, v10
	v_fma_f32 v11, v22, v32, v11
	v_fma_f32 v12, v22, v34, v12
	v_fma_f32 v13, v22, v36, v13
	v_fma_f32 v10, -v54, v31, v10
	v_fma_f32 v11, -v54, v33, v11
	v_fma_f32 v12, -v54, v35, v12
	v_fma_f32 v13, -v54, v37, v13
	ds_read_b64 v[28:29], v6 offset:9768
	ds_read_b64 v[38:39], v8 offset:4736
	ds_read_b128 v[30:33], v7 offset:4736
	ds_read_b128 v[34:37], v7 offset:4752
	s_waitcnt lgkmcnt(8)
	v_mul_f32_e32 v55, v47, v41
	v_mul_f32_e32 v56, v47, v40
	v_fma_f32 v22, v46, v40, -v55
	v_fma_f32 v54, v46, v41, v56
	v_fma_f32 v10, v22, v42, v10
	v_fma_f32 v11, v22, v44, v11
	v_fma_f32 v12, v22, v50, v12
	v_fma_f32 v13, v22, v52, v13
	v_fma_f32 v10, -v54, v43, v10
	v_fma_f32 v11, -v54, v45, v11
	v_fma_f32 v12, -v54, v51, v12
	v_fma_f32 v13, -v54, v53, v13
	ds_read_b64 v[40:41], v6 offset:10032
	ds_read_b64 v[46:47], v8 offset:4864
	ds_read_b128 v[42:45], v7 offset:4864
	ds_read_b128 v[50:53], v7 offset:4880
	s_waitcnt lgkmcnt(8)
	v_mul_f32_e32 v55, v21, v15
	v_mul_f32_e32 v56, v21, v14
	v_fma_f32 v22, v20, v14, -v55
	v_fma_f32 v54, v20, v15, v56
	v_fma_f32 v10, v22, v16, v10
	v_fma_f32 v11, v22, v18, v11
	v_fma_f32 v12, v22, v24, v12
	v_fma_f32 v13, v22, v26, v13
	v_fma_f32 v10, -v54, v17, v10
	v_fma_f32 v11, -v54, v19, v11
	v_fma_f32 v12, -v54, v25, v12
	v_fma_f32 v13, -v54, v27, v13
	ds_read_b64 v[14:15], v6 offset:10296
	ds_read_b64 v[20:21], v8 offset:4992
	ds_read_b128 v[16:19], v7 offset:4992
	ds_read_b128 v[24:27], v7 offset:5008
	s_waitcnt lgkmcnt(8)
	v_mul_f32_e32 v55, v39, v29
	v_mul_f32_e32 v56, v39, v28
	v_fma_f32 v22, v38, v28, -v55
	v_fma_f32 v54, v38, v29, v56
	v_fma_f32 v10, v22, v30, v10
	v_fma_f32 v11, v22, v32, v11
	v_fma_f32 v12, v22, v34, v12
	v_fma_f32 v13, v22, v36, v13
	v_fma_f32 v10, -v54, v31, v10
	v_fma_f32 v11, -v54, v33, v11
	v_fma_f32 v12, -v54, v35, v12
	v_fma_f32 v13, -v54, v37, v13
	ds_read_b64 v[28:29], v6 offset:10560
	ds_read_b64 v[38:39], v8 offset:5120
	ds_read_b128 v[30:33], v7 offset:5120
	ds_read_b128 v[34:37], v7 offset:5136
	s_waitcnt lgkmcnt(8)
	v_mul_f32_e32 v55, v47, v41
	v_mul_f32_e32 v56, v47, v40
	v_fma_f32 v22, v46, v40, -v55
	v_fma_f32 v54, v46, v41, v56
	v_fma_f32 v10, v22, v42, v10
	v_fma_f32 v11, v22, v44, v11
	v_fma_f32 v12, v22, v50, v12
	v_fma_f32 v13, v22, v52, v13
	v_fma_f32 v10, -v54, v43, v10
	v_fma_f32 v11, -v54, v45, v11
	v_fma_f32 v12, -v54, v51, v12
	v_fma_f32 v13, -v54, v53, v13
	ds_read_b64 v[40:41], v6 offset:10824
	ds_read_b64 v[46:47], v8 offset:5248
	ds_read_b128 v[42:45], v7 offset:5248
	ds_read_b128 v[50:53], v7 offset:5264
	s_waitcnt lgkmcnt(8)
	v_mul_f32_e32 v55, v21, v15
	v_mul_f32_e32 v56, v21, v14
	v_fma_f32 v22, v20, v14, -v55
	v_fma_f32 v54, v20, v15, v56
	v_fma_f32 v10, v22, v16, v10
	v_fma_f32 v11, v22, v18, v11
	v_fma_f32 v12, v22, v24, v12
	v_fma_f32 v13, v22, v26, v13
	v_fma_f32 v10, -v54, v17, v10
	v_fma_f32 v11, -v54, v19, v11
	v_fma_f32 v12, -v54, v25, v12
	v_fma_f32 v13, -v54, v27, v13
	ds_read_b64 v[14:15], v6 offset:11088
	ds_read_b64 v[20:21], v8 offset:5376
	ds_read_b128 v[16:19], v7 offset:5376
	ds_read_b128 v[24:27], v7 offset:5392
	s_waitcnt lgkmcnt(8)
	v_mul_f32_e32 v55, v39, v29
	v_mul_f32_e32 v56, v39, v28
	v_fma_f32 v22, v38, v28, -v55
	v_fma_f32 v54, v38, v29, v56
	v_fma_f32 v10, v22, v30, v10
	v_fma_f32 v11, v22, v32, v11
	v_fma_f32 v12, v22, v34, v12
	v_fma_f32 v13, v22, v36, v13
	v_fma_f32 v10, -v54, v31, v10
	v_fma_f32 v11, -v54, v33, v11
	v_fma_f32 v12, -v54, v35, v12
	v_fma_f32 v13, -v54, v37, v13
	ds_read_b64 v[28:29], v6 offset:11352
	ds_read_b64 v[38:39], v8 offset:5504
	ds_read_b128 v[30:33], v7 offset:5504
	ds_read_b128 v[34:37], v7 offset:5520
	s_waitcnt lgkmcnt(8)
	v_mul_f32_e32 v55, v47, v41
	v_mul_f32_e32 v56, v47, v40
	v_fma_f32 v22, v46, v40, -v55
	v_fma_f32 v54, v46, v41, v56
	v_fma_f32 v10, v22, v42, v10
	v_fma_f32 v11, v22, v44, v11
	v_fma_f32 v12, v22, v50, v12
	v_fma_f32 v13, v22, v52, v13
	v_fma_f32 v10, -v54, v43, v10
	v_fma_f32 v11, -v54, v45, v11
	v_fma_f32 v12, -v54, v51, v12
	v_fma_f32 v13, -v54, v53, v13
	ds_read_b64 v[40:41], v6 offset:11616
	ds_read_b64 v[46:47], v8 offset:5632
	ds_read_b128 v[42:45], v7 offset:5632
	ds_read_b128 v[50:53], v7 offset:5648
	s_waitcnt lgkmcnt(8)
	v_mul_f32_e32 v55, v21, v15
	v_mul_f32_e32 v56, v21, v14
	v_fma_f32 v22, v20, v14, -v55
	v_fma_f32 v54, v20, v15, v56
	v_fma_f32 v10, v22, v16, v10
	v_fma_f32 v11, v22, v18, v11
	v_fma_f32 v12, v22, v24, v12
	v_fma_f32 v13, v22, v26, v13
	v_fma_f32 v10, -v54, v17, v10
	v_fma_f32 v11, -v54, v19, v11
	v_fma_f32 v12, -v54, v25, v12
	v_fma_f32 v13, -v54, v27, v13
	ds_read_b64 v[14:15], v6 offset:11880
	ds_read_b64 v[20:21], v8 offset:5760
	ds_read_b128 v[16:19], v7 offset:5760
	ds_read_b128 v[24:27], v7 offset:5776
	s_waitcnt lgkmcnt(8)
	v_mul_f32_e32 v55, v39, v29
	v_mul_f32_e32 v56, v39, v28
	v_fma_f32 v22, v38, v28, -v55
	v_fma_f32 v54, v38, v29, v56
	v_fma_f32 v10, v22, v30, v10
	v_fma_f32 v11, v22, v32, v11
	v_fma_f32 v12, v22, v34, v12
	v_fma_f32 v13, v22, v36, v13
	v_fma_f32 v10, -v54, v31, v10
	v_fma_f32 v11, -v54, v33, v11
	v_fma_f32 v12, -v54, v35, v12
	v_fma_f32 v13, -v54, v37, v13
	ds_read_b64 v[28:29], v6 offset:12144
	ds_read_b64 v[38:39], v8 offset:5888
	ds_read_b128 v[30:33], v7 offset:5888
	ds_read_b128 v[34:37], v7 offset:5904
	s_waitcnt lgkmcnt(8)
	v_mul_f32_e32 v55, v47, v41
	v_mul_f32_e32 v56, v47, v40
	v_fma_f32 v22, v46, v40, -v55
	v_fma_f32 v54, v46, v41, v56
	v_fma_f32 v10, v22, v42, v10
	v_fma_f32 v11, v22, v44, v11
	v_fma_f32 v12, v22, v50, v12
	v_fma_f32 v13, v22, v52, v13
	v_fma_f32 v10, -v54, v43, v10
	v_fma_f32 v11, -v54, v45, v11
	v_fma_f32 v12, -v54, v51, v12
	v_fma_f32 v13, -v54, v53, v13
	ds_read_b64 v[40:41], v6 offset:12408
	ds_read_b64 v[46:47], v8 offset:6016
	ds_read_b128 v[42:45], v7 offset:6016
	ds_read_b128 v[50:53], v7 offset:6032
	s_waitcnt lgkmcnt(8)
	v_mul_f32_e32 v55, v21, v15
	v_mul_f32_e32 v56, v21, v14
	v_fma_f32 v22, v20, v14, -v55
	v_fma_f32 v54, v20, v15, v56
	v_fma_f32 v10, v22, v16, v10
	v_fma_f32 v11, v22, v18, v11
	v_fma_f32 v12, v22, v24, v12
	v_fma_f32 v13, v22, v26, v13
	v_fma_f32 v10, -v54, v17, v10
	v_fma_f32 v11, -v54, v19, v11
	v_fma_f32 v12, -v54, v25, v12
	v_fma_f32 v13, -v54, v27, v13
	ds_read_b64 v[14:15], v6 offset:12672
	ds_read_b64 v[20:21], v8 offset:6144
	ds_read_b128 v[16:19], v7 offset:6144
	ds_read_b128 v[24:27], v7 offset:6160
	s_waitcnt lgkmcnt(8)
	v_mul_f32_e32 v55, v39, v29
	v_mul_f32_e32 v56, v39, v28
	v_fma_f32 v22, v38, v28, -v55
	v_fma_f32 v54, v38, v29, v56
	v_fma_f32 v10, v22, v30, v10
	v_fma_f32 v11, v22, v32, v11
	v_fma_f32 v12, v22, v34, v12
	v_fma_f32 v13, v22, v36, v13
	v_fma_f32 v10, -v54, v31, v10
	v_fma_f32 v11, -v54, v33, v11
	v_fma_f32 v12, -v54, v35, v12
	v_fma_f32 v13, -v54, v37, v13
	ds_read_b64 v[28:29], v6 offset:12936
	ds_read_b64 v[38:39], v8 offset:6272
	ds_read_b128 v[30:33], v7 offset:6272
	ds_read_b128 v[34:37], v7 offset:6288
	s_waitcnt lgkmcnt(8)
	v_mul_f32_e32 v55, v47, v41
	v_mul_f32_e32 v56, v47, v40
	v_fma_f32 v22, v46, v40, -v55
	v_fma_f32 v54, v46, v41, v56
	v_fma_f32 v10, v22, v42, v10
	v_fma_f32 v11, v22, v44, v11
	v_fma_f32 v12, v22, v50, v12
	v_fma_f32 v13, v22, v52, v13
	v_fma_f32 v10, -v54, v43, v10
	v_fma_f32 v11, -v54, v45, v11
	v_fma_f32 v12, -v54, v51, v12
	v_fma_f32 v13, -v54, v53, v13
	ds_read_b64 v[40:41], v6 offset:13200
	ds_read_b64 v[46:47], v8 offset:6400
	ds_read_b128 v[42:45], v7 offset:6400
	ds_read_b128 v[50:53], v7 offset:6416
	s_waitcnt lgkmcnt(8)
	v_mul_f32_e32 v55, v21, v15
	v_mul_f32_e32 v56, v21, v14
	v_fma_f32 v22, v20, v14, -v55
	v_fma_f32 v54, v20, v15, v56
	v_fma_f32 v10, v22, v16, v10
	v_fma_f32 v11, v22, v18, v11
	v_fma_f32 v12, v22, v24, v12
	v_fma_f32 v13, v22, v26, v13
	v_fma_f32 v10, -v54, v17, v10
	v_fma_f32 v11, -v54, v19, v11
	v_fma_f32 v12, -v54, v25, v12
	v_fma_f32 v13, -v54, v27, v13
	ds_read_b64 v[14:15], v6 offset:13464
	ds_read_b64 v[20:21], v8 offset:6528
	ds_read_b128 v[16:19], v7 offset:6528
	ds_read_b128 v[24:27], v7 offset:6544
	s_waitcnt lgkmcnt(8)
	v_mul_f32_e32 v55, v39, v29
	v_mul_f32_e32 v56, v39, v28
	v_fma_f32 v22, v38, v28, -v55
	v_fma_f32 v54, v38, v29, v56
	v_fma_f32 v10, v22, v30, v10
	v_fma_f32 v11, v22, v32, v11
	v_fma_f32 v12, v22, v34, v12
	v_fma_f32 v13, v22, v36, v13
	v_fma_f32 v10, -v54, v31, v10
	v_fma_f32 v11, -v54, v33, v11
	v_fma_f32 v12, -v54, v35, v12
	v_fma_f32 v13, -v54, v37, v13
	ds_read_b64 v[28:29], v6 offset:13728
	ds_read_b64 v[38:39], v8 offset:6656
	ds_read_b128 v[30:33], v7 offset:6656
	ds_read_b128 v[34:37], v7 offset:6672
	s_waitcnt lgkmcnt(8)
	v_mul_f32_e32 v55, v47, v41
	v_mul_f32_e32 v56, v47, v40
	v_fma_f32 v22, v46, v40, -v55
	v_fma_f32 v54, v46, v41, v56
	v_fma_f32 v10, v22, v42, v10
	v_fma_f32 v11, v22, v44, v11
	v_fma_f32 v12, v22, v50, v12
	v_fma_f32 v13, v22, v52, v13
	v_fma_f32 v10, -v54, v43, v10
	v_fma_f32 v11, -v54, v45, v11
	v_fma_f32 v12, -v54, v51, v12
	v_fma_f32 v13, -v54, v53, v13
	ds_read_b64 v[40:41], v6 offset:13992
	ds_read_b64 v[46:47], v8 offset:6784
	ds_read_b128 v[42:45], v7 offset:6784
	ds_read_b128 v[50:53], v7 offset:6800
	s_waitcnt lgkmcnt(8)
	v_mul_f32_e32 v55, v21, v15
	v_mul_f32_e32 v56, v21, v14
	v_fma_f32 v22, v20, v14, -v55
	v_fma_f32 v54, v20, v15, v56
	v_fma_f32 v10, v22, v16, v10
	v_fma_f32 v11, v22, v18, v11
	v_fma_f32 v12, v22, v24, v12
	v_fma_f32 v13, v22, v26, v13
	v_fma_f32 v10, -v54, v17, v10
	v_fma_f32 v11, -v54, v19, v11
	v_fma_f32 v12, -v54, v25, v12
	v_fma_f32 v13, -v54, v27, v13
	ds_read_b64 v[14:15], v6 offset:14256
	ds_read_b64 v[20:21], v8 offset:6912
	ds_read_b128 v[16:19], v7 offset:6912
	ds_read_b128 v[24:27], v7 offset:6928
	s_waitcnt lgkmcnt(8)
	v_mul_f32_e32 v55, v39, v29
	v_mul_f32_e32 v56, v39, v28
	v_fma_f32 v22, v38, v28, -v55
	v_fma_f32 v54, v38, v29, v56
	v_fma_f32 v10, v22, v30, v10
	v_fma_f32 v11, v22, v32, v11
	v_fma_f32 v12, v22, v34, v12
	v_fma_f32 v13, v22, v36, v13
	v_fma_f32 v10, -v54, v31, v10
	v_fma_f32 v11, -v54, v33, v11
	v_fma_f32 v12, -v54, v35, v12
	v_fma_f32 v13, -v54, v37, v13
	ds_read_b64 v[28:29], v6 offset:14520
	ds_read_b64 v[38:39], v8 offset:7040
	ds_read_b128 v[30:33], v7 offset:7040
	ds_read_b128 v[34:37], v7 offset:7056
	s_waitcnt lgkmcnt(8)
	v_mul_f32_e32 v55, v47, v41
	v_mul_f32_e32 v56, v47, v40
	v_fma_f32 v22, v46, v40, -v55
	v_fma_f32 v54, v46, v41, v56
	v_fma_f32 v10, v22, v42, v10
	v_fma_f32 v11, v22, v44, v11
	v_fma_f32 v12, v22, v50, v12
	v_fma_f32 v13, v22, v52, v13
	v_fma_f32 v10, -v54, v43, v10
	v_fma_f32 v11, -v54, v45, v11
	v_fma_f32 v12, -v54, v51, v12
	v_fma_f32 v13, -v54, v53, v13
	ds_read_b64 v[40:41], v6 offset:14784
	ds_read_b64 v[46:47], v8 offset:7168
	ds_read_b128 v[42:45], v7 offset:7168
	ds_read_b128 v[50:53], v7 offset:7184
	s_waitcnt lgkmcnt(8)
	v_mul_f32_e32 v55, v21, v15
	v_mul_f32_e32 v56, v21, v14
	v_fma_f32 v22, v20, v14, -v55
	v_fma_f32 v54, v20, v15, v56
	v_fma_f32 v10, v22, v16, v10
	v_fma_f32 v11, v22, v18, v11
	v_fma_f32 v12, v22, v24, v12
	v_fma_f32 v13, v22, v26, v13
	v_fma_f32 v10, -v54, v17, v10
	v_fma_f32 v11, -v54, v19, v11
	v_fma_f32 v12, -v54, v25, v12
	v_fma_f32 v13, -v54, v27, v13
	ds_read_b64 v[14:15], v6 offset:15048
	ds_read_b64 v[20:21], v8 offset:7296
	ds_read_b128 v[16:19], v7 offset:7296
	ds_read_b128 v[24:27], v7 offset:7312
	s_waitcnt lgkmcnt(8)
	v_mul_f32_e32 v55, v39, v29
	v_mul_f32_e32 v56, v39, v28
	v_fma_f32 v22, v38, v28, -v55
	v_fma_f32 v54, v38, v29, v56
	v_fma_f32 v10, v22, v30, v10
	v_fma_f32 v11, v22, v32, v11
	v_fma_f32 v12, v22, v34, v12
	v_fma_f32 v13, v22, v36, v13
	v_fma_f32 v10, -v54, v31, v10
	v_fma_f32 v11, -v54, v33, v11
	v_fma_f32 v12, -v54, v35, v12
	v_fma_f32 v13, -v54, v37, v13
	ds_read_b64 v[28:29], v6 offset:15312
	ds_read_b64 v[38:39], v8 offset:7424
	ds_read_b128 v[30:33], v7 offset:7424
	ds_read_b128 v[34:37], v7 offset:7440
	s_waitcnt lgkmcnt(8)
	v_mul_f32_e32 v55, v47, v41
	v_mul_f32_e32 v56, v47, v40
	v_fma_f32 v22, v46, v40, -v55
	v_fma_f32 v54, v46, v41, v56
	v_fma_f32 v10, v22, v42, v10
	v_fma_f32 v11, v22, v44, v11
	v_fma_f32 v12, v22, v50, v12
	v_fma_f32 v13, v22, v52, v13
	v_fma_f32 v10, -v54, v43, v10
	v_fma_f32 v11, -v54, v45, v11
	v_fma_f32 v12, -v54, v51, v12
	v_fma_f32 v13, -v54, v53, v13
	ds_read_b64 v[40:41], v6 offset:15576
	ds_read_b64 v[46:47], v8 offset:7552
	ds_read_b128 v[42:45], v7 offset:7552
	ds_read_b128 v[50:53], v7 offset:7568
	s_waitcnt lgkmcnt(8)
	v_mul_f32_e32 v55, v21, v15
	v_mul_f32_e32 v56, v21, v14
	v_fma_f32 v22, v20, v14, -v55
	v_fma_f32 v54, v20, v15, v56
	v_fma_f32 v10, v22, v16, v10
	v_fma_f32 v11, v22, v18, v11
	v_fma_f32 v12, v22, v24, v12
	v_fma_f32 v13, v22, v26, v13
	v_fma_f32 v10, -v54, v17, v10
	v_fma_f32 v11, -v54, v19, v11
	v_fma_f32 v12, -v54, v25, v12
	v_fma_f32 v13, -v54, v27, v13
	ds_read_b64 v[14:15], v6 offset:15840
	ds_read_b64 v[20:21], v8 offset:7680
	ds_read_b128 v[16:19], v7 offset:7680
	ds_read_b128 v[24:27], v7 offset:7696
	s_waitcnt lgkmcnt(8)
	v_mul_f32_e32 v55, v39, v29
	v_mul_f32_e32 v56, v39, v28
	v_fma_f32 v22, v38, v28, -v55
	v_fma_f32 v54, v38, v29, v56
	v_fma_f32 v10, v22, v30, v10
	v_fma_f32 v11, v22, v32, v11
	v_fma_f32 v12, v22, v34, v12
	v_fma_f32 v13, v22, v36, v13
	v_fma_f32 v10, -v54, v31, v10
	v_fma_f32 v11, -v54, v33, v11
	v_fma_f32 v12, -v54, v35, v12
	v_fma_f32 v13, -v54, v37, v13
	ds_read_b64 v[28:29], v6 offset:16104
	ds_read_b64 v[38:39], v8 offset:7808
	ds_read_b128 v[30:33], v7 offset:7808
	ds_read_b128 v[34:37], v7 offset:7824
	s_waitcnt lgkmcnt(8)
	v_mul_f32_e32 v55, v47, v41
	v_mul_f32_e32 v56, v47, v40
	v_fma_f32 v22, v46, v40, -v55
	v_fma_f32 v54, v46, v41, v56
	v_fma_f32 v10, v22, v42, v10
	v_fma_f32 v11, v22, v44, v11
	v_fma_f32 v12, v22, v50, v12
	v_fma_f32 v13, v22, v52, v13
	v_fma_f32 v10, -v54, v43, v10
	v_fma_f32 v11, -v54, v45, v11
	v_fma_f32 v12, -v54, v51, v12
	v_fma_f32 v13, -v54, v53, v13
	ds_read_b64 v[40:41], v6 offset:16368
	ds_read_b64 v[46:47], v8 offset:7936
	ds_read_b128 v[42:45], v7 offset:7936
	ds_read_b128 v[50:53], v7 offset:7952
	s_waitcnt lgkmcnt(8)
	v_mul_f32_e32 v55, v21, v15
	v_mul_f32_e32 v56, v21, v14
	v_fma_f32 v22, v20, v14, -v55
	v_fma_f32 v54, v20, v15, v56
	v_fma_f32 v10, v22, v16, v10
	v_fma_f32 v11, v22, v18, v11
	v_fma_f32 v12, v22, v24, v12
	v_fma_f32 v13, v22, v26, v13
	v_fma_f32 v10, -v54, v17, v10
	v_fma_f32 v11, -v54, v19, v11
	v_fma_f32 v12, -v54, v25, v12
	v_fma_f32 v13, -v54, v27, v13
	ds_read_b64 v[14:15], v6 offset:16632
	ds_read_b64 v[20:21], v8 offset:8064
	ds_read_b128 v[16:19], v7 offset:8064
	ds_read_b128 v[24:27], v7 offset:8080
	s_waitcnt lgkmcnt(8)
	v_mul_f32_e32 v55, v39, v29
	v_mul_f32_e32 v56, v39, v28
	v_fma_f32 v22, v38, v28, -v55
	v_fma_f32 v54, v38, v29, v56
	v_fma_f32 v10, v22, v30, v10
	v_fma_f32 v11, v22, v32, v11
	v_fma_f32 v12, v22, v34, v12
	v_fma_f32 v13, v22, v36, v13
	v_fma_f32 v10, -v54, v31, v10
	v_fma_f32 v11, -v54, v33, v11
	v_fma_f32 v12, -v54, v35, v12
	v_fma_f32 v13, -v54, v37, v13
	s_waitcnt lgkmcnt(4)
	v_mul_f32_e32 v55, v47, v41
	v_mul_f32_e32 v56, v47, v40
	v_fma_f32 v22, v46, v40, -v55
	v_fma_f32 v54, v46, v41, v56
	v_fma_f32 v10, v22, v42, v10
	v_fma_f32 v11, v22, v44, v11
	v_fma_f32 v12, v22, v50, v12
	v_fma_f32 v13, v22, v52, v13
	v_fma_f32 v10, -v54, v43, v10
	v_fma_f32 v11, -v54, v45, v11
	v_fma_f32 v12, -v54, v51, v12
	v_fma_f32 v13, -v54, v53, v13
	s_waitcnt lgkmcnt(0)
	v_mul_f32_e32 v55, v21, v15
	v_mul_f32_e32 v56, v21, v14
	v_fma_f32 v22, v20, v14, -v55
	v_fma_f32 v54, v20, v15, v56
	v_fma_f32 v10, v22, v16, v10
	v_fma_f32 v11, v22, v18, v11
	v_fma_f32 v12, v22, v24, v12
	v_fma_f32 v13, v22, v26, v13
	v_fma_f32 v10, -v54, v17, v10
	v_fma_f32 v11, -v54, v19, v11
	v_fma_f32 v12, -v54, v25, v12
	v_fma_f32 v13, -v54, v27, v13
	s_lshl_b32 s18, s16, 5
	s_add_u32 s18, s18, s17
	s_lshl_b32 s18, s18, 10
	s_add_u32 s8, s6, s18
	s_addc_u32 s9, s7, 0
	s_add_u32 s8, s8, 0xc4000
	s_addc_u32 s9, s9, 0
	v_and_b32_e32 v9, 63, v224
	v_lshlrev_b32_e32 v9, 4, v9
	global_store_dwordx4 v9, v[10:13], s[8:9]
	s_mov_b64 s[10:11], s[78:79]
	s_mov_b64 s[8:9], s[78:79]
	s_mov_b64 s[12:13], s[78:79]
	s_mov_b64 s[14:15], s[78:79]
	s_mov_b64 s[16:17], s[78:79]
	v_mov_b32_e32 v0, v224
	v_mbcnt_lo_u32_b32 v72, -1, 0
	v_readfirstlane_b32 s4, v0
	s_ashr_i32 s18, s4, 6
	s_add_i32 s27, s18, s70
	s_cmp_gt_i32 s27, 0x11fff
	s_mul_i32 s75, s64, 24
	s_cbranch_scc1 .LBB0_175
	v_mbcnt_hi_u32_b32 v1, -1, v72
	v_and_b32_e32 v2, 64, v1
	v_add_u32_e32 v3, 64, v2
	v_xor_b32_e32 v4, 1, v1
	v_cmp_lt_i32_e32 vcc, v4, v3
	s_load_dwordx2 s[20:21], s[14:15], 0x100
	s_load_dwordx2 s[4:5], s[10:11], 0x0
	s_load_dwordx2 s[6:7], s[8:9], 0x10
	s_load_dwordx2 s[22:23], s[12:13], 0x30
	s_load_dwordx2 s[24:25], s[16:17], 0x100
	v_cndmask_b32_e32 v4, v1, v4, vcc
	v_lshlrev_b32_e32 v73, 2, v4
	v_xor_b32_e32 v4, 2, v1
	v_cmp_lt_i32_e32 vcc, v4, v3
	v_and_b32_e32 v0, 63, v0
	v_mov_b32_e32 v5, 0
	v_cndmask_b32_e32 v4, v1, v4, vcc
	v_lshlrev_b32_e32 v74, 2, v4
	v_xor_b32_e32 v4, 4, v1
	v_cmp_lt_i32_e32 vcc, v4, v3
	s_waitcnt lgkmcnt(0)
	s_add_u32 s13, s20, 0x63c8000
	s_addc_u32 s15, s21, 0
	v_cndmask_b32_e32 v4, v1, v4, vcc
	v_lshlrev_b32_e32 v75, 2, v4
	v_xor_b32_e32 v4, 8, v1
	v_cmp_lt_i32_e32 vcc, v4, v3
	s_lshl_b32 s10, s64, 5
	s_mov_b64 s[16:17], 0x85b4000
	v_cndmask_b32_e32 v4, v1, v4, vcc
	v_lshlrev_b32_e32 v76, 2, v4
	v_xor_b32_e32 v4, 16, v1
	v_cmp_lt_i32_e32 vcc, v4, v3
	s_ashr_i32 s8, s18, 31
	s_ashr_i32 s11, s70, 31
	v_cndmask_b32_e32 v4, v1, v4, vcc
	v_lshlrev_b32_e32 v77, 2, v4
	v_xor_b32_e32 v4, 32, v1
	v_cmp_lt_i32_e32 vcc, v4, v3
	v_lshlrev_b32_e32 v2, 2, v0
	v_or_b32_e32 v6, 0x100, v2
	v_cndmask_b32_e32 v1, v1, v4, vcc
	v_lshlrev_b32_e32 v4, 4, v0
	v_lshl_add_u64 v[64:65], s[22:23], 0, v[4:5]
	v_lshlrev_b32_e32 v4, 3, v0
	v_lshl_add_u64 v[12:13], s[24:25], 0, v[4:5]
	v_lshl_add_u64 v[66:67], v[12:13], 0, s[16:17]
	s_add_u32 s16, s18, s70
	s_addc_u32 s17, s8, s11
	s_lshl_b64 s[16:17], s[16:17], 11
	s_add_u32 s16, s24, s16
	s_addc_u32 s17, s25, s17
	v_or_b32_e32 v8, 0x200, v2
	v_or_b32_e32 v10, 0x300, v2
	v_lshl_add_u64 v[4:5], s[16:17], 0, v[4:5]
	s_mov_b64 s[16:17], 0x85b4400
	s_ashr_i32 s11, s10, 31
	s_mov_b32 s9, 0
	v_lshlrev_b32_e32 v78, 2, v1
	v_lshl_add_u64 v[68:69], v[4:5], 0, s[16:17]
	s_lshl_b64 s[10:11], s[10:11], 11
	s_lshl_b32 s44, s64, 4
	v_lshlrev_b32_e32 v79, 4, v0
	v_lshlrev_b32_e32 v80, 2, v2
	v_lshlrev_b32_e32 v81, 2, v6
	v_lshlrev_b32_e32 v82, 2, v8
	v_lshlrev_b32_e32 v83, 2, v10
	s_mov_b32 s12, 0x3a800000
	s_mov_b32 s14, 0x358637bd
	s_mov_b32 s45, 0x800000
	s_branch .LBB0_159
